# m3 per-lane address registers hoisted out of the chunk loop
# speedup vs baseline: 1.0045x; 1.0045x over previous
.LBB0_446:
	s_or_b64 exec, exec, s[0:1]
	s_mov_b64 s[2:3], s[72:73]
	v_readlane_b32 s12, v254, 35
	v_readlane_b32 s0, v254, 60
	s_and_b64 vcc, exec, s[58:59]
	s_waitcnt lgkmcnt(0)
	s_barrier
	v_readlane_b32 s1, v254, 61
	s_cbranch_vccz .LBB0_494
	s_load_dwordx2 s[0:1], s[2:3], 0x88
	s_load_dwordx8 s[4:11], s[2:3], 0x48
	s_nop 0
	s_load_dwordx2 s[2:3], s[2:3], 0x68
	s_mov_b32 s39, s70
	s_waitcnt lgkmcnt(0)
	s_add_u32 s14, s0, 0xc000000
	s_addc_u32 s15, s1, 0
	s_add_u32 s33, s0, 0xe000000
	s_addc_u32 s36, s1, 0
	s_lshl_b32 s16, s12, 12
	s_ashr_i32 s17, s16, 31
	s_lshl_b64 s[16:17], s[16:17], 2
	s_add_u32 s16, s4, s16
	s_addc_u32 s17, s5, s17
	s_lshl_b32 s4, s12, 10
	s_ashr_i32 s5, s4, 31
	s_lshl_b64 s[4:5], s[4:5], 2
	s_add_u32 s18, s6, s4
	s_addc_u32 s19, s7, s5
	s_add_u32 s37, s0, 0x18200000
	s_addc_u32 s38, s1, 0
	s_lshl_b32 s4, s12, 7
	s_ashr_i32 s5, s4, 31
	s_lshl_b64 s[4:5], s[4:5], 2
	s_add_u32 s20, s2, s4
	s_addc_u32 s21, s3, s5
	s_add_u32 s22, s0, 0x12000000
	s_addc_u32 s23, s1, 0
	s_add_u32 s24, s0, 0x4000000
	s_addc_u32 s25, s1, 0
	s_lshl_b32 s2, s12, 3
	s_ashr_i32 s3, s2, 31
	s_lshl_b64 s[2:3], s[2:3], 2
	s_add_u32 s26, s10, s2
	s_addc_u32 s27, s11, s3
	s_add_u32 s28, s8, s2
	s_addc_u32 s29, s9, s3
	s_add_u32 s30, s0, 0x18000000
	s_addc_u32 s31, s1, 0
	v_lshlrev_b32_e32 v0, 4, v194
	global_load_dwordx4 v[4:7], v0, s[16:17]
	s_add_u32 s90, s16, 0x2000
	s_addc_u32 s91, s17, 0
	global_load_dwordx4 v[8:11], v0, s[90:91]
	v_cmp_gt_u32_e32 vcc, 0x100, v194
	s_and_saveexec_b64 s[92:93], vcc
	global_load_dwordx4 v[12:15], v0, s[18:19]
	s_mov_b64 exec, s[92:93]
	v_add_u32_e32 v1, 0x1a000, v0
	s_waitcnt vmcnt(0)
	ds_write_b128 v1, v[4:7]
	ds_write_b128 v1, v[8:11] offset:8192
	s_and_saveexec_b64 s[92:93], vcc
	ds_write_b128 v1, v[12:15] offset:16384
	s_mov_b64 exec, s[92:93]
	s_waitcnt lgkmcnt(0)
	s_barrier
	v_lshrrev_b32_e32 v209, 3, v194
	v_and_b32_e32 v210, 7, v194
	v_lshlrev_b32_e32 v211, 4, v210
	v_lshl_or_b32 v190, v209, 15, v211
	v_lshl_or_b32 v192, v209, 11, v211
	v_add_u32_e32 v193, 0x1000, v192
	v_lshlrev_b32_e32 v208, 5, v210
	s_branch .LBB0_449

.LBB0_449:
	s_ashr_i32 s2, s39, 10
	s_and_b32 s41, s39, 0x7f
	s_ashr_i32 s3, s2, 31
	v_mov_b32_e32 v23, v194
	s_lshl_b64 s[34:35], s[2:3], 13
	s_lshl_b32 s2, s41, 6
	s_bfe_u32 s42, s39, 0x30007
	v_readfirstlane_b32 s40, v23
	s_or_b32 s34, s34, s2
	v_lshlrev_b32_e32 v191, 4, v23
	s_lshl_b32 s90, s42, 7
	s_or_b32 s90, s90, 0x400
	s_lshl_b64 s[52:53], s[34:35], 1
	s_add_u32 s52, s33, s52
	s_addc_u32 s53, s36, s53
	s_lshl_b32 s91, s90, 15
	s_add_u32 s52, s52, s91
	s_addc_u32 s53, s53, 0
	s_add_u32 s54, s52, 0x200000
	s_addc_u32 s55, s53, 0
	global_load_dwordx4 v[44:47], v190, s[52:53]
	global_load_dwordx4 v[48:51], v190, s[54:55]
	s_mul_i32 s92, s39, 0x4080
	s_mul_hi_i32 s93, s39, 0x4080
	s_add_u32 s92, s37, s92
	s_addc_u32 s93, s38, s93
	global_load_dwordx4 v[52:55], v191, s[92:93]
	s_add_u32 s94, s92, 0x2000
	s_addc_u32 s95, s93, 0
	global_load_dwordx4 v[56:59], v191, s[94:95]
	s_add_u32 s94, s92, 0x4000
	s_addc_u32 s95, s93, 0
	v_cmp_gt_u32_e32 vcc, 8, v23
	s_and_saveexec_b64 s[96:97], vcc
	global_load_dwordx4 v[60:63], v191, s[94:95]
	s_mov_b64 exec, s[96:97]
	s_sub_u32 s92, s34, 3
	s_subb_u32 s93, s35, 0
	s_lshl_b64 s[92:93], s[92:93], 11
	s_add_u32 s92, s14, s92
	s_addc_u32 s93, s15, s93
	s_lshl_b32 s91, s42, 7
	s_add_u32 s92, s92, s91
	s_addc_u32 s93, s93, 0
	s_cmp_lg_u32 s41, 0
	s_cselect_b64 s[54:55], -1, 0
	v_cmp_lt_u32_e32 vcc, 2, v209
	s_or_b64 s[46:47], s[54:55], vcc
	v_cmp_lt_u32_e32 vcc, 1, v209
	s_or_b64 s[48:49], s[54:55], vcc
	v_cmp_lt_u32_e32 vcc, 0, v209
	s_or_b64 s[50:51], s[54:55], vcc
	s_mov_b64 s[96:97], exec
	s_and_b64 exec, s[96:97], s[46:47]
	global_load_dwordx4 v[80:83], v192, s[92:93]
	global_load_dwordx4 v[128:131], v192, s[92:93] offset:1024
	s_and_b64 exec, s[96:97], s[48:49]
	global_load_dwordx4 v[92:95], v192, s[92:93] offset:2048
	global_load_dwordx4 v[140:143], v192, s[92:93] offset:3072
	s_and_b64 exec, s[96:97], s[50:51]
	global_load_dwordx4 v[104:107], v193, s[92:93]
	global_load_dwordx4 v[152:155], v193, s[92:93] offset:1024
	s_mov_b64 exec, s[96:97]
	global_load_dwordx4 v[116:119], v193, s[92:93] offset:2048
	global_load_dwordx4 v[178:181], v193, s[92:93] offset:3072
	s_lshr_b32 s90, s40, 6
	s_lshl_b32 s90, s90, 3
	s_add_u32 s90, s34, s90
	s_addc_u32 s91, s35, 0
	s_lshl_b64 s[90:91], s[90:91], 11
	s_add_u32 s90, s22, s90
	s_addc_u32 s91, s23, s91
	s_lshl_b32 s92, s42, 8
	v_and_b32_e32 v232, 63, v23
	v_lshlrev_b32_e32 v233, 3, v232
	v_lshl_or_b32 v232, v232, 2, s92
	global_load_dword v224, v232, s[90:91]
	global_load_dword v225, v232, s[90:91] offset:2048
	s_add_u32 s90, s90, 0x1000
	s_addc_u32 s91, s91, 0
	global_load_dword v226, v232, s[90:91]
	global_load_dword v227, v232, s[90:91] offset:2048
	s_add_u32 s90, s90, 0x1000
	s_addc_u32 s91, s91, 0
	global_load_dword v228, v232, s[90:91]
	global_load_dword v229, v232, s[90:91] offset:2048
	s_add_u32 s90, s90, 0x1000
	s_addc_u32 s91, s91, 0
	global_load_dword v230, v232, s[90:91]
	global_load_dword v231, v232, s[90:91] offset:2048
	global_load_dwordx2 v[234:235], v233, s[20:21]
	s_cmp_gt_u32 s40, 63
	v_and_b32_e32 v22, 63, v23
	s_cbranch_scc1 .LBB0_451
	v_or_b32_e32 v0, s34, v22
	v_mov_b32_e32 v1, s35
	v_lshlrev_b64 v[0:1], 6, v[0:1]
	v_lshl_add_u64 v[0:1], s[30:31], 0, v[0:1]
	s_lshl_b32 s86, s42, 2
	v_lshl_add_u64 v[0:1], v[0:1], 0, s[86:87]
	v_mov_b32_e32 v3, s86
	global_load_dword v2, v[0:1], off offset:32
	global_load_dword v4, v3, s[26:27]
	s_nop 0
	global_load_dword v0, v[0:1], off
	s_nop 0
	global_load_dword v1, v3, s[28:29]
	s_lshl_b32 s98, s39, 4
	s_add_u32 s98, s0, s98
	s_addc_u32 s99, s1, 0
	v_mov_b32_e32 v41, 0x18100000
	global_load_dword v42, v41, s[98:99] offset:8
	s_mov_b32 s2, 0x3f317218
	s_waitcnt vmcnt(2)
	v_add_f32_e32 v2, v2, v4
	s_waitcnt vmcnt(0)
	v_add_f32_e32 v1, v0, v1
	v_min_f32_e32 v0, 0, v2
	v_mul_f32_e64 v2, |v2|, s79
	v_exp_f32_e32 v4, v2
	s_nop 0
	v_add_f32_e32 v5, 1.0, v4
	v_add_f32_e32 v2, -1.0, v5
	v_sub_f32_e32 v3, v2, v5
	v_add_f32_e32 v3, 1.0, v3
	v_sub_f32_e32 v2, v4, v2
	v_add_f32_e32 v6, v2, v3
	v_frexp_mant_f32_e32 v2, v5
	v_cmp_gt_f32_e32 vcc, s85, v2
	v_cvt_f64_f32_e32 v[2:3], v5
	v_frexp_exp_i32_f64_e32 v2, v[2:3]
	v_subbrev_co_u32_e32 v2, vcc, 0, v2, vcc
	v_sub_u32_e32 v3, 0, v2
	v_ldexp_f32 v5, v5, v3
	v_ldexp_f32 v3, v6, v3
	v_add_f32_e32 v6, -1.0, v5
	v_add_f32_e32 v7, 1.0, v6
	v_sub_f32_e32 v7, v5, v7
	v_add_f32_e32 v7, v3, v7
	v_add_f32_e32 v8, v6, v7
	v_sub_f32_e32 v6, v8, v6
	v_sub_f32_e32 v6, v7, v6
	v_add_f32_e32 v7, 1.0, v5
	v_add_f32_e32 v9, -1.0, v7
	v_sub_f32_e32 v5, v5, v9
	v_add_f32_e32 v3, v3, v5
	v_add_f32_e32 v5, v7, v3
	v_sub_f32_e32 v7, v5, v7
	v_sub_f32_e32 v3, v3, v7
	v_rcp_f32_e32 v7, v5
	v_cvt_f32_i32_e32 v2, v2
	v_mul_f32_e32 v9, v8, v7
	v_mul_f32_e32 v10, v5, v9
	v_fma_f32 v11, v9, v5, -v10
	v_fmac_f32_e32 v11, v9, v3
	v_add_f32_e32 v12, v10, v11
	v_sub_f32_e32 v13, v8, v12
	v_sub_f32_e32 v8, v8, v13
	v_sub_f32_e32 v10, v12, v10
	v_sub_f32_e32 v8, v8, v12
	v_add_f32_e32 v6, v6, v8
	v_sub_f32_e32 v8, v10, v11
	v_add_f32_e32 v6, v8, v6
	v_add_f32_e32 v8, v13, v6
	v_mul_f32_e32 v10, v7, v8
	v_mul_f32_e32 v11, v5, v10
	v_fma_f32 v5, v10, v5, -v11
	v_fmac_f32_e32 v5, v10, v3
	v_sub_f32_e32 v3, v13, v8
	v_add_f32_e32 v3, v6, v3
	v_add_f32_e32 v6, v11, v5
	v_sub_f32_e32 v12, v8, v6
	v_sub_f32_e32 v8, v8, v12
	v_sub_f32_e32 v11, v6, v11
	v_sub_f32_e32 v6, v8, v6
	v_add_f32_e32 v3, v3, v6
	v_sub_f32_e32 v5, v11, v5
	v_add_f32_e32 v3, v5, v3
	v_add_f32_e32 v5, v9, v10
	v_add_f32_e32 v3, v12, v3
	v_sub_f32_e32 v6, v5, v9
	v_mul_f32_e32 v3, v7, v3
	v_sub_f32_e32 v6, v10, v6
	v_add_f32_e32 v3, v6, v3
	v_mul_f32_e32 v9, 0x3f317218, v2
	v_add_f32_e32 v6, v5, v3
	v_fma_f32 v10, v2, s2, -v9
	v_mul_f32_e32 v7, v6, v6
	v_fmac_f32_e32 v10, 0xb102e308, v2
	v_sub_f32_e32 v2, v6, v5
	v_fmamk_f32 v8, v7, 0x3e9b6dac, v200
	v_sub_f32_e32 v2, v3, v2
	v_add_f32_e32 v3, v9, v10
	v_fmaak_f32 v8, v7, v8, 0x3f2aaada
	v_sub_f32_e32 v5, v3, v9
	v_ldexp_f32 v9, v6, 1
	v_mul_f32_e32 v6, v6, v7
	v_mul_f32_e32 v6, v6, v8
	v_add_f32_e32 v7, v9, v6
	v_sub_f32_e32 v8, v7, v9
	v_ldexp_f32 v2, v2, 1
	v_sub_f32_e32 v6, v6, v8
	v_add_f32_e32 v2, v2, v6
	v_add_f32_e32 v6, v7, v2
	v_sub_f32_e32 v7, v6, v7
	v_sub_f32_e32 v2, v2, v7
	v_add_f32_e32 v7, v3, v6
	v_sub_f32_e32 v8, v7, v3
	v_sub_f32_e32 v9, v7, v8
	v_sub_f32_e32 v5, v10, v5
	v_sub_f32_e32 v3, v3, v9
	v_sub_f32_e32 v6, v6, v8
	v_add_f32_e32 v3, v6, v3
	v_add_f32_e32 v6, v5, v2
	v_sub_f32_e32 v8, v6, v5
	v_sub_f32_e32 v9, v6, v8
	v_sub_f32_e32 v5, v5, v9
	v_sub_f32_e32 v2, v2, v8
	v_add_f32_e32 v3, v6, v3
	v_add_f32_e32 v2, v2, v5
	v_add_f32_e32 v5, v7, v3
	v_sub_f32_e32 v6, v5, v7
	v_sub_f32_e32 v3, v3, v6
	v_add_f32_e32 v2, v2, v3
	s_mov_b32 s2, 0x7f800000
	v_add_f32_e32 v2, v5, v2
	v_cmp_neq_f32_e32 vcc, s2, v4
	s_mov_b32 s2, 0x33800000
	v_add_u32_e32 v3, -1, v201
	v_cndmask_b32_e32 v2, v202, v2, vcc
	v_cmp_ngt_f32_e32 vcc, -1.0, v4
	s_nop 1
	v_cndmask_b32_e32 v2, v203, v2, vcc
	v_cmp_neq_f32_e32 vcc, -1.0, v4
	s_nop 1
	v_cndmask_b32_e32 v2, v204, v2, vcc
	v_cmp_lt_f32_e64 vcc, |v4|, s2
	s_lshl_b32 s2, s39, 2
	s_ashr_i32 s3, s2, 31
	v_cndmask_b32_e32 v2, v2, v4, vcc
	v_sub_f32_e32 v0, v0, v2
	v_mov_b32_e32 v4, v0
	s_nop 1
	v_add_f32_dpp v4, v0, v4 row_shr:1 row_mask:0xf bank_mask:0xf
	v_add_f32_dpp v4, v0, v4 row_shr:2 row_mask:0xf bank_mask:0xf
	v_add_f32_dpp v4, v0, v4 row_shr:3 row_mask:0xf bank_mask:0xf
	s_nop 1
	v_add_f32_dpp v4, v4, v4 row_shr:4 row_mask:0xf bank_mask:0xe
	s_nop 1
	v_add_f32_dpp v4, v4, v4 row_shr:8 row_mask:0xf bank_mask:0xc
	s_nop 1
	v_add_f32_dpp v4, v4, v4 row_bcast:15 row_mask:0xa bank_mask:0xf
	s_nop 1
	v_add_f32_dpp v4, v4, v4 row_bcast:31 row_mask:0xc bank_mask:0xf
	v_mov_b32_e32 v0, v4
	v_sub_f32_e32 v1, v1, v0
	v_mov_b32_e32 v3, v1
	s_nop 1
	v_max_f32_dpp v3, v1, v3 row_shr:1 row_mask:0xf bank_mask:0xf
	v_max_f32_dpp v3, v1, v3 row_shr:2 row_mask:0xf bank_mask:0xf
	v_max_f32_dpp v3, v1, v3 row_shr:3 row_mask:0xf bank_mask:0xf
	s_nop 1
	v_max_f32_dpp v3, v3, v3 row_shr:4 row_mask:0xf bank_mask:0xe
	s_nop 1
	v_max_f32_dpp v3, v3, v3 row_shr:8 row_mask:0xf bank_mask:0xc
	s_nop 1
	v_max_f32_dpp v3, v3, v3 row_bcast:15 row_mask:0xa bank_mask:0xf
	s_nop 1
	v_max_f32_dpp v3, v3, v3 row_bcast:31 row_mask:0xc bank_mask:0xf
	v_mov_b32_e32 v2, v3
	v_max_f32_e32 v2, v2, v2
	s_waitcnt vmcnt(0)
	v_mov_b32_e32 v3, v42
	v_max_f32_e32 v4, v3, v3
	v_max_f32_e32 v2, v4, v2
	v_lshl_add_u32 v4, v22, 2, 0
	v_add_u32_e32 v4, 0x19200, v4
	ds_write2st64_b32 v4, v1, v2 offset1:1
	v_sub_f32_e32 v1, v3, v2
	v_add_f32_e32 v0, v0, v2
	v_mul_f32_e32 v1, 0x3fb8aa3b, v1
	v_mul_f32_e32 v0, 0xbfb8aa3b, v0
	v_exp_f32_e32 v1, v1
	v_exp_f32_e32 v0, v0
	ds_write2st64_b32 v4, v1, v0 offset0:2 offset1:3
